# attention steady loop: each step's first score MFMA issues right behind the opening barrier (slot arithmetic and first V fragment reads follow it)
# speedup vs baseline: 1.0030x; 1.0030x over previous
.LBB0_310:
	v_mfma_f32_32x32x16_bf16 v[128:143], v[204:207], v[172:175], v[64:79]
	s_lshl_b32 s14, s14, 1
	v_add_u32_e32 v217, s14, v244
	ds_read_b64_tr_b16 v[208:209], v217 offset:24576
	ds_read_b64_tr_b16 v[210:211], v217 offset:25088
	v_add_f32_e32 v112, v96, v97
	v_add_f32_e32 v112, v98, v112
	v_add_f32_e32 v112, v99, v112
	v_add_f32_e32 v112, v100, v112
	v_add_f32_e32 v112, v101, v112
	v_cvt_pk_bf16_f32 v164, v96, v97
	v_cvt_pk_bf16_f32 v165, v98, v99
	ds_read_b64_tr_b16 v[96:97], v217 offset:28672
	ds_read_b64_tr_b16 v[98:99], v217 offset:29184
	v_add_f32_e32 v112, v102, v112
	v_add_f32_e32 v112, v103, v112
	v_add_f32_e32 v112, v104, v112
	v_add_f32_e32 v144, v105, v112
	v_mfma_f32_32x32x16_bf16 v[112:127], v[200:203], v[172:175], v[64:79]
	v_cvt_pk_bf16_f32 v166, v100, v101
	v_cvt_pk_bf16_f32 v167, v102, v103
	ds_read_b64_tr_b16 v[100:101], v217 offset:25600
	ds_read_b64_tr_b16 v[102:103], v217 offset:26112
	v_mfma_f32_32x32x16_bf16 v[128:143], v[196:199], v[168:171], v[128:143]
	v_add_f32_e32 v144, v106, v144
	v_add_f32_e32 v144, v107, v144
	v_add_f32_e32 v144, v108, v144
	v_add_f32_e32 v144, v109, v144
	v_cvt_pk_bf16_f32 v156, v104, v105
	v_cvt_pk_bf16_f32 v157, v106, v107
	ds_read_b64_tr_b16 v[104:105], v217 offset:29696
	ds_read_b64_tr_b16 v[106:107], v217 offset:30208
	v_mfma_f32_32x32x16_bf16 v[112:127], v[192:195], v[168:171], v[112:127]
	v_add_f32_e32 v144, v110, v144
	v_add_f32_e32 v144, v111, v144
	v_add_f32_e32 v144, v80, v144
	v_add_f32_e32 v144, v81, v144
	v_cvt_pk_bf16_f32 v158, v108, v109
	v_cvt_pk_bf16_f32 v159, v110, v111
	ds_read_b64_tr_b16 v[108:109], v217 offset:26624
	ds_read_b64_tr_b16 v[110:111], v217 offset:27136
	v_mfma_f32_32x32x16_bf16 v[128:143], v[188:191], v[160:163], v[128:143]
	v_add_f32_e32 v144, v82, v144
	v_add_f32_e32 v144, v83, v144
	v_add_f32_e32 v144, v84, v144
	v_add_f32_e32 v144, v85, v144
	v_cvt_pk_bf16_f32 v148, v80, v81
	v_cvt_pk_bf16_f32 v149, v82, v83
	ds_read_b64_tr_b16 v[80:81], v217 offset:30720
	ds_read_b64_tr_b16 v[82:83], v217 offset:31232
	v_mfma_f32_32x32x16_bf16 v[112:127], v[184:187], v[160:163], v[112:127]
	v_add_f32_e32 v144, v86, v144
	v_add_f32_e32 v144, v87, v144
	v_add_f32_e32 v144, v88, v144
	v_add_f32_e32 v144, v89, v144
	v_cvt_pk_bf16_f32 v150, v84, v85
	v_cvt_pk_bf16_f32 v151, v86, v87
	ds_read_b64_tr_b16 v[84:85], v217 offset:27648
	ds_read_b64_tr_b16 v[86:87], v217 offset:28160
	v_mfma_f32_32x32x16_bf16 v[128:143], v[180:183], v[152:155], v[128:143]
	v_add_f32_e32 v144, v90, v144
	v_add_f32_e32 v144, v91, v144
	v_add_f32_e32 v144, v92, v144
	v_add_f32_e32 v180, v93, v144
	v_cvt_pk_bf16_f32 v144, v88, v89
	v_cvt_pk_bf16_f32 v145, v90, v91
	ds_read_b64_tr_b16 v[88:89], v217 offset:31744
	ds_read_b64_tr_b16 v[90:91], v217 offset:32256
	v_mfma_f32_32x32x16_bf16 v[112:127], v[176:179], v[152:155], v[112:127]
	v_add_f32_e32 v146, v94, v180
	v_add_f32_e32 v176, v95, v146
	v_cvt_pk_bf16_f32 v146, v92, v93
	v_cvt_pk_bf16_f32 v147, v94, v95
	s_add_i32 m0, s24, s63
	s_mov_b32 s14, s32
	s_mov_b32 s15, s70
	global_load_lds_dwordx4 v212, s[14:15]
	s_lshl_b32 s14, s22, 1
	s_add_i32 s14, s14, s64
	s_mov_b32 m0, s14
	s_add_i32 s14, s14, 0x1f80
	global_load_lds_dwordx4 v226, s[98:99]
	s_mov_b32 m0, s14
	s_nop 0
	global_load_lds_dwordx4 v226, s[98:99] offset:128
	s_waitcnt lgkmcnt(12)
	v_mfma_f32_32x32x16_bf16 v[32:47], v[164:167], v[208:211], v[32:47]
	v_max_f32_e32 v222, v128, v129
	v_max3_f32 v223, v130, v131, v113
	v_max3_f32 v222, v222, v112, v114
	v_max3_f32 v222, v222, v115, v132
	ds_read_b64_tr_b16 v[92:93], v217 offset:32768
	ds_read_b64_tr_b16 v[94:95], v217 offset:33280
	v_mfma_f32_32x32x16_bf16 v[48:63], v[164:167], v[96:99], v[48:63]
	v_max3_f32 v223, v223, v134, v135
	v_max3_f32 v222, v222, v133, v116
	v_max3_f32 v223, v223, v118, v119
	v_max3_f32 v222, v222, v117, v136
	ds_read_b64_tr_b16 v[96:97], v217 offset:36864
	ds_read_b64_tr_b16 v[98:99], v217 offset:37376
	s_waitcnt lgkmcnt(12)
	v_mfma_f32_32x32x16_bf16 v[32:47], v[156:159], v[100:103], v[32:47]
	v_max3_f32 v223, v223, v138, v139
	v_max3_f32 v222, v222, v137, v120
	v_max3_f32 v223, v223, v122, v123
	v_max3_f32 v222, v222, v121, v140
	ds_read_b64_tr_b16 v[100:101], v217 offset:33792
	ds_read_b64_tr_b16 v[102:103], v217 offset:34304
	v_mfma_f32_32x32x16_bf16 v[48:63], v[156:159], v[104:107], v[48:63]
	v_max3_f32 v223, v223, v142, v143
	v_max3_f32 v222, v222, v141, v124
	v_max3_f32 v223, v223, v126, v127
	v_max3_f32 v222, v222, v125, v223
	ds_read_b64_tr_b16 v[104:105], v217 offset:37888
	ds_read_b64_tr_b16 v[106:107], v217 offset:38400
	s_waitcnt lgkmcnt(12)
	v_mfma_f32_32x32x16_bf16 v[32:47], v[148:151], v[108:111], v[32:47]
	v_mov_b32_e32 v223, v222
	v_add_f32_e32 v215, v249, v176
	s_nop 0
	v_permlane32_swap_b32_e32 v222, v223
	v_max_f32_e32 v222, v222, v223
	v_cmp_lt_f32_e32 vcc, s33, v222
	s_nop 0
	s_mov_b64 s[20:21], vcc
	s_cbranch_vccnz .LBB0_318

.LBB0_313:
	v_mfma_f32_32x32x16_bf16 v[96:111], v[80:83], v[172:175], v[64:79]
	s_add_i32 s14, s22, 0x2000
	s_cmpk_lg_i32 s22, 0x4000
	s_cselect_b32 s66, s14, 0
	s_lshl_b32 s14, s24, 1
	v_add_u32_e32 v209, s14, v244
	ds_read_b64_tr_b16 v[188:189], v209 offset:24576
	ds_read_b64_tr_b16 v[190:191], v209 offset:25088
	v_add_f32_e32 v84, v128, v129
	v_add_f32_e32 v84, v130, v84
	v_add_f32_e32 v84, v131, v84
	v_add_f32_e32 v84, v132, v84
	v_add_f32_e32 v84, v133, v84
	v_cvt_pk_bf16_f32 v164, v128, v129
	v_cvt_pk_bf16_f32 v165, v130, v131
	ds_read_b64_tr_b16 v[128:129], v209 offset:28672
	ds_read_b64_tr_b16 v[130:131], v209 offset:29184
	v_add_f32_e32 v80, v134, v84
	v_add_f32_e32 v80, v135, v80
	v_add_f32_e32 v80, v136, v80
	v_add_f32_e32 v144, v137, v80
	v_mfma_f32_32x32x16_bf16 v[80:95], v[200:203], v[172:175], v[64:79]
	v_cvt_pk_bf16_f32 v166, v132, v133
	v_cvt_pk_bf16_f32 v167, v134, v135
	ds_read_b64_tr_b16 v[132:133], v209 offset:25600
	ds_read_b64_tr_b16 v[134:135], v209 offset:26112
	v_mfma_f32_32x32x16_bf16 v[96:111], v[204:207], v[168:171], v[96:111]
	v_add_f32_e32 v144, v138, v144
	v_add_f32_e32 v144, v139, v144
	v_add_f32_e32 v144, v140, v144
	v_add_f32_e32 v144, v141, v144
	v_cvt_pk_bf16_f32 v156, v136, v137
	v_cvt_pk_bf16_f32 v157, v138, v139
	ds_read_b64_tr_b16 v[136:137], v209 offset:29696
	ds_read_b64_tr_b16 v[138:139], v209 offset:30208
	v_mfma_f32_32x32x16_bf16 v[80:95], v[196:199], v[168:171], v[80:95]
	v_add_f32_e32 v144, v142, v144
	v_add_f32_e32 v144, v143, v144
	v_add_f32_e32 v144, v112, v144
	v_add_f32_e32 v144, v113, v144
	v_cvt_pk_bf16_f32 v158, v140, v141
	v_cvt_pk_bf16_f32 v159, v142, v143
	ds_read_b64_tr_b16 v[140:141], v209 offset:26624
	ds_read_b64_tr_b16 v[142:143], v209 offset:27136
	v_mfma_f32_32x32x16_bf16 v[96:111], v[192:195], v[160:163], v[96:111]
	v_add_f32_e32 v144, v114, v144
	v_add_f32_e32 v144, v115, v144
	v_add_f32_e32 v144, v116, v144
	v_add_f32_e32 v144, v117, v144
	v_cvt_pk_bf16_f32 v148, v112, v113
	v_cvt_pk_bf16_f32 v149, v114, v115
	ds_read_b64_tr_b16 v[112:113], v209 offset:30720
	ds_read_b64_tr_b16 v[114:115], v209 offset:31232
	v_mfma_f32_32x32x16_bf16 v[80:95], v[184:187], v[160:163], v[80:95]
	v_add_f32_e32 v144, v118, v144
	v_add_f32_e32 v144, v119, v144
	v_add_f32_e32 v144, v120, v144
	v_add_f32_e32 v144, v121, v144
	v_cvt_pk_bf16_f32 v150, v116, v117
	v_cvt_pk_bf16_f32 v151, v118, v119
	ds_read_b64_tr_b16 v[116:117], v209 offset:27648
	ds_read_b64_tr_b16 v[118:119], v209 offset:28160
	v_mfma_f32_32x32x16_bf16 v[96:111], v[180:183], v[152:155], v[96:111]
	v_add_f32_e32 v144, v122, v144
	v_add_f32_e32 v144, v123, v144
	v_add_f32_e32 v144, v124, v144
	v_add_f32_e32 v180, v125, v144
	v_cvt_pk_bf16_f32 v144, v120, v121
	v_cvt_pk_bf16_f32 v145, v122, v123
	ds_read_b64_tr_b16 v[120:121], v209 offset:31744
	ds_read_b64_tr_b16 v[122:123], v209 offset:32256
	v_mfma_f32_32x32x16_bf16 v[80:95], v[176:179], v[152:155], v[80:95]
	v_add_f32_e32 v146, v126, v180
	v_add_f32_e32 v176, v127, v146
	v_cvt_pk_bf16_f32 v146, v124, v125
	v_cvt_pk_bf16_f32 v147, v126, v127
	s_add_i32 m0, s22, s63
	s_add_u32 s14, s32, 0x20000
	s_addc_u32 s15, s70, 0
	global_load_lds_dwordx4 v212, s[14:15]
	s_lshl_b32 s20, s66, 1
	s_add_i32 s20, s20, s64
	s_add_u32 s14, s98, 0x20000
	s_addc_u32 s15, s99, 0
	s_mov_b32 m0, s20
	s_add_i32 s20, s20, 0x1f80
	global_load_lds_dwordx4 v226, s[14:15]
	s_mov_b32 m0, s20
	s_nop 0
	global_load_lds_dwordx4 v226, s[14:15] offset:128
	s_waitcnt lgkmcnt(12)
	v_mfma_f32_32x32x16_bf16 v[32:47], v[164:167], v[188:191], v[32:47]
	v_max_f32_e32 v224, v96, v97
	v_max3_f32 v225, v98, v99, v81
	v_max3_f32 v224, v224, v80, v82
	v_max3_f32 v224, v224, v83, v100
	ds_read_b64_tr_b16 v[124:125], v209 offset:32768
	ds_read_b64_tr_b16 v[126:127], v209 offset:33280
	v_mfma_f32_32x32x16_bf16 v[48:63], v[164:167], v[128:131], v[48:63]
	v_max3_f32 v225, v225, v102, v103
	v_max3_f32 v224, v224, v101, v84
	v_max3_f32 v225, v225, v86, v87
	v_max3_f32 v224, v224, v85, v104
	ds_read_b64_tr_b16 v[128:129], v209 offset:36864
	ds_read_b64_tr_b16 v[130:131], v209 offset:37376
	s_waitcnt lgkmcnt(12)
	v_mfma_f32_32x32x16_bf16 v[32:47], v[156:159], v[132:135], v[32:47]
	v_max3_f32 v225, v225, v106, v107
	v_max3_f32 v224, v224, v105, v88
	v_max3_f32 v225, v225, v90, v91
	v_max3_f32 v224, v224, v89, v108
	ds_read_b64_tr_b16 v[132:133], v209 offset:33792
	ds_read_b64_tr_b16 v[134:135], v209 offset:34304
	v_mfma_f32_32x32x16_bf16 v[48:63], v[156:159], v[136:139], v[48:63]
	v_max3_f32 v225, v225, v110, v111
	v_max3_f32 v224, v224, v109, v92
	v_max3_f32 v225, v225, v94, v95
	v_max3_f32 v224, v224, v93, v225
	ds_read_b64_tr_b16 v[136:137], v209 offset:37888
	ds_read_b64_tr_b16 v[138:139], v209 offset:38400
	s_waitcnt lgkmcnt(12)
	v_mfma_f32_32x32x16_bf16 v[32:47], v[148:151], v[140:143], v[32:47]
	v_mov_b32_e32 v225, v224
	v_add_f32_e32 v249, v215, v176
	s_nop 0
	v_permlane32_swap_b32_e32 v224, v225
	v_max_f32_e32 v224, v224, v225
	v_cmp_lt_f32_e32 vcc, s33, v224
	s_nop 0
	s_mov_b64 s[20:21], vcc
	s_cbranch_vccnz .LBB0_321
